# v39: v36 + RG-LRU scan passes: -log2(e) scale of the sigmoids / exp(-sp8 r) folded into the per-channel constants ((acc+b)*K -> fma(acc,K,b*K), computed once per run); f32 as before
# speedup vs baseline: 1.0069x; 1.0001x over previous
.LBB0_383:
	s_or_b64 exec, exec, s[18:19]
	s_cmp_lt_u32 s26, 4
	s_cselect_b32 s50, 17, 16
	s_add_i32 s4, s16, s27
	s_mul_hi_i32 s51, s4, 0x84
	s_mul_i32 s52, s4, 0x84
	s_lshl_b32 s4, s17, 2
	v_lshl_add_u64 v[94:95], v[88:89], 0, s[4:5]
	s_mov_b64 s[18:19], 0x2000
	v_add_u32_e32 v76, s17, v116
	v_mov_b32_e32 v77, v96
	v_lshl_add_u64 v[98:99], v[94:95], 0, s[18:19]
	s_mov_b64 s[18:19], 0x6000
	v_lshl_add_u64 v[100:101], v[94:95], 0, s[68:69]
	v_lshl_add_u64 v[102:103], v[94:95], 0, s[18:19]
	v_lshl_add_u64 v[104:105], v[90:91], 0, s[4:5]
	v_lshl_add_u64 v[106:107], v[76:77], 2, s[8:9]
	s_mov_b32 s53, 0
	s_waitcnt vmcnt(0)
	v_mul_f32_e32 v125, 0xbfb8aa3b, v125
	v_mul_f32_e32 v126, 0xbfb8aa3b, v126
	v_mul_f32_e32 v129, 0xbfb8aa3b, v129
	v_mul_f32_e32 v130, 0xbfb8aa3b, v130
	v_mul_f32_e32 v127, 0xbfb8aa3b, v127
	v_mul_f32_e32 v128, 0xbfb8aa3b, v128
	s_branch .LBB0_385

.LBB0_401:
	v_mad_u32_u24 v81, v80, s3, v115
	ds_read_b128 v[76:79], v81
	ds_read_b128 v[146:149], v81 offset:64
	v_add_u32_e32 v80, -16, v80
	s_waitcnt lgkmcnt(1)
	v_mfma_f32_16x16x32_bf16 v[134:137], v[76:79], v[0:3], 0
	v_mfma_f32_16x16x32_bf16 v[138:141], v[76:79], v[16:19], 0
	v_mfma_f32_16x16x32_bf16 v[142:145], v[76:79], v[32:35], 0
	v_mfma_f32_16x16x32_bf16 v[76:79], v[76:79], v[48:51], 0
	s_waitcnt lgkmcnt(0)
	v_mfma_f32_16x16x32_bf16 v[134:137], v[146:149], v[4:7], v[134:137]
	v_mfma_f32_16x16x32_bf16 v[138:141], v[146:149], v[20:23], v[138:141]
	v_mfma_f32_16x16x32_bf16 v[142:145], v[146:149], v[36:39], v[142:145]
	v_mfma_f32_16x16x32_bf16 v[76:79], v[146:149], v[52:55], v[76:79]
	ds_read_b128 v[146:149], v81 offset:128
	s_waitcnt lgkmcnt(0)
	v_mfma_f32_16x16x32_bf16 v[134:137], v[146:149], v[8:11], v[134:137]
	v_mfma_f32_16x16x32_bf16 v[138:141], v[146:149], v[24:27], v[138:141]
	v_mfma_f32_16x16x32_bf16 v[142:145], v[146:149], v[40:43], v[142:145]
	v_mfma_f32_16x16x32_bf16 v[76:79], v[146:149], v[56:59], v[76:79]
	ds_read_b128 v[146:149], v81 offset:192
	s_waitcnt lgkmcnt(0)
	v_mfma_f32_16x16x32_bf16 v[134:137], v[146:149], v[12:15], v[134:137]
	s_nop 7
	v_fmamk_f32 v81, v134, 0xbfb8aa3b, v125
	s_nop 0
	v_exp_f32_e32 v81, v81
	v_mfma_f32_16x16x32_bf16 v[142:145], v[146:149], v[44:47], v[142:145]
	v_add_f32_e32 v81, 1.0, v81
	v_rcp_f32_e32 v81, v81
	v_mfma_f32_16x16x32_bf16 v[138:141], v[146:149], v[28:31], v[138:141]
	s_nop 4
	v_fmamk_f32 v82, v142, 0xbfb8aa3b, v126
	s_nop 0
	v_mul_f32_e32 v81, v81, v127
	s_nop 0
	v_exp_f32_e32 v83, v81
	v_exp_f32_e32 v82, v82
	v_fmamk_f32 v97, v143, 0xbfb8aa3b, v126
	v_fma_f32 v81, -v83, v83, 1.0
	v_add_f32_e32 v82, 1.0, v82
	v_max_f32_e32 v81, 0, v81
	v_rcp_f32_e32 v82, v82
	v_sqrt_f32_e32 v81, v81
	v_exp_f32_e32 v97, v97
	v_mfma_f32_16x16x32_bf16 v[76:79], v[146:149], v[60:63], v[76:79]
	v_mul_f32_e32 v134, v82, v81
	v_fmamk_f32 v82, v135, 0xbfb8aa3b, v125
	s_nop 0
	v_exp_f32_e32 v82, v82
	v_add_f32_e32 v97, 1.0, v97
	v_rcp_f32_e32 v97, v97
	v_add_u32_e32 v81, s4, v122
	v_add_f32_e32 v82, 1.0, v82
	v_rcp_f32_e32 v82, v82
	ds_read2_b32 v[146:147], v81 offset1:16
	ds_read2_b32 v[150:151], v81 offset0:132 offset1:148
	v_add_u32_e32 v81, 0x400, v81
	v_mul_f32_e32 v82, v82, v127
	v_exp_f32_e32 v143, v82
	ds_read2_b32 v[156:157], v81 offset0:140 offset1:156
	ds_read2_b32 v[154:155], v81 offset0:8 offset1:24
	s_waitcnt lgkmcnt(2)
	v_mov_b32_e32 v142, v150
	v_fma_f32 v82, -v143, v143, 1.0
	v_max_f32_e32 v82, 0, v82
	v_sqrt_f32_e32 v82, v82
	s_waitcnt lgkmcnt(0)
	v_mov_b32_e32 v152, v154
	v_fmamk_f32 v76, v76, 0xbfb8aa3b, v129
	s_nop 0
	v_mul_f32_e32 v148, v97, v82
	v_fmamk_f32 v82, v136, 0xbfb8aa3b, v125
	s_nop 0
	v_exp_f32_e32 v82, v82
	v_fmamk_f32 v97, v144, 0xbfb8aa3b, v126
	s_nop 0
	v_exp_f32_e32 v97, v97
	v_add_f32_e32 v82, 1.0, v82
	v_rcp_f32_e32 v82, v82
	v_exp_f32_e32 v76, v76
	v_add_f32_e32 v97, 1.0, v97
	v_rcp_f32_e32 v97, v97
	v_mul_f32_e32 v82, v82, v127
	v_exp_f32_e32 v153, v82
	v_add_f32_e32 v76, 1.0, v76
	v_rcp_f32_e32 v76, v76
	v_fmamk_f32 v77, v77, 0xbfb8aa3b, v129
	v_fma_f32 v82, -v153, v153, 1.0
	v_max_f32_e32 v82, 0, v82
	v_sqrt_f32_e32 v82, v82
	v_exp_f32_e32 v77, v77
	v_fmamk_f32 v78, v78, 0xbfb8aa3b, v129
	v_mul_f32_e32 v136, v97, v82
	v_fmamk_f32 v82, v137, 0xbfb8aa3b, v125
	v_exp_f32_e32 v82, v82
	v_fmamk_f32 v97, v145, 0xbfb8aa3b, v126
	v_exp_f32_e32 v97, v97
	v_add_f32_e32 v82, 1.0, v82
	v_rcp_f32_e32 v82, v82
	v_mov_b32_e32 v145, v156
	v_add_f32_e32 v97, 1.0, v97
	v_rcp_f32_e32 v97, v97
	v_mul_f32_e32 v82, v82, v127
	v_exp_f32_e32 v144, v82
	v_add_f32_e32 v77, 1.0, v77
	v_rcp_f32_e32 v77, v77
	v_fma_f32 v82, -v144, v144, 1.0
	v_max_f32_e32 v82, 0, v82
	v_sqrt_f32_e32 v82, v82
	v_mul_f32_e32 v81, v144, v153
	v_mul_f32_e32 v81, v143, v81
	v_mul_f32_e32 v81, v83, v81
	v_mul_f32_e32 v97, v97, v82
	v_mul_f32_e32 v82, 0, v144
	v_pk_fma_f32 v[158:159], v[144:145], v[96:97], v[82:83] op_sel_hi:[1,1,0]
	v_mul_f32_e32 v82, v154, v136
	v_mov_b32_e32 v137, v159
	v_pk_fma_f32 v[136:137], v[152:153], v[136:137], v[82:83] op_sel_hi:[1,1,0]
	v_mul_f32_e32 v82, v150, v148
	v_mov_b32_e32 v149, v137
	v_pk_fma_f32 v[136:137], v[142:143], v[148:149], v[82:83] op_sel_hi:[1,1,0]
	v_mov_b32_e32 v82, v146
	v_mov_b32_e32 v135, v137
	v_mul_f32_e32 v136, v83, v137
	v_pk_fma_f32 v[134:135], v[82:83], v[134:135], v[136:137] op_sel_hi:[1,1,0]
	ds_bpermute_b32 v82, v132, v81
	ds_bpermute_b32 v142, v131, v81
	ds_bpermute_b32 v146, v133, v81
	ds_bpermute_b32 v150, v93, v81
	v_fmamk_f32 v81, v138, 0xbfb8aa3b, v130
	v_exp_f32_e32 v81, v81
	v_exp_f32_e32 v78, v78
	v_fmamk_f32 v79, v79, 0xbfb8aa3b, v129
	v_add_f32_e32 v81, 1.0, v81
	v_rcp_f32_e32 v81, v81
	v_add_f32_e32 v78, 1.0, v78
	v_rcp_f32_e32 v78, v78
	v_exp_f32_e32 v79, v79
	v_mul_f32_e32 v81, v81, v128
	v_exp_f32_e32 v153, v81
	v_add_f32_e32 v79, 1.0, v79
	v_rcp_f32_e32 v79, v79
	v_mov_b32_e32 v97, v157
	v_fma_f32 v81, -v153, v153, 1.0
	v_max_f32_e32 v81, 0, v81
	v_sqrt_f32_e32 v81, v81
	v_mov_b32_e32 v158, v155
	v_mov_b32_e32 v152, v147
	ds_bpermute_b32 v136, v132, v134
	v_mul_f32_e32 v76, v76, v81
	v_fmamk_f32 v81, v139, 0xbfb8aa3b, v130
	v_exp_f32_e32 v81, v81
	ds_bpermute_b32 v144, v131, v134
	ds_bpermute_b32 v148, v133, v134
	ds_bpermute_b32 v134, v93, v134
	v_add_f32_e32 v81, 1.0, v81
	v_rcp_f32_e32 v81, v81
	s_addk_i32 s4, 0xdf00
	s_cmpk_lg_i32 s4, 0x6700
	v_mul_f32_e32 v81, v81, v128
	s_nop 0
	v_exp_f32_e32 v139, v81
	s_nop 0
	v_fma_f32 v81, -v139, v139, 1.0
	v_max_f32_e32 v81, 0, v81
	v_sqrt_f32_e32 v81, v81
	s_nop 0
	v_mul_f32_e32 v154, v77, v81
	v_fmamk_f32 v77, v140, 0xbfb8aa3b, v130
	s_nop 0
	v_exp_f32_e32 v77, v77
	s_nop 0
	v_add_f32_e32 v77, 1.0, v77
	v_rcp_f32_e32 v77, v77
	s_nop 0
	v_mul_f32_e32 v77, v77, v128
	s_nop 0
	v_exp_f32_e32 v159, v77
	s_nop 0
	v_fma_f32 v77, -v159, v159, 1.0
	v_max_f32_e32 v77, 0, v77
	v_sqrt_f32_e32 v77, v77
	s_nop 0
	v_mul_f32_e32 v78, v78, v77
	v_fmamk_f32 v77, v141, 0xbfb8aa3b, v130
	s_nop 0
	v_exp_f32_e32 v77, v77
	s_nop 0
	v_add_f32_e32 v77, 1.0, v77
	v_rcp_f32_e32 v77, v77
	s_nop 0
	v_mul_f32_e32 v77, v77, v128
	s_nop 0
	v_exp_f32_e32 v140, v77
	s_nop 0
	v_fma_f32 v77, -v140, v140, 1.0
	v_max_f32_e32 v77, 0, v77
	v_sqrt_f32_e32 v77, v77
	v_mul_f32_e32 v138, 0, v140
	v_mul_f32_e32 v141, v79, v77
	v_pk_fma_f32 v[156:157], v[140:141], v[96:97], v[138:139] op_sel_hi:[1,1,0]
	v_mul_f32_e32 v138, v78, v155
	v_mov_b32_e32 v79, v157
	v_pk_fma_f32 v[78:79], v[78:79], v[158:159], v[138:139] op_sel_hi:[1,1,0]
	v_mov_b32_e32 v138, v151
	v_mov_b32_e32 v155, v79
	v_mul_f32_e32 v78, v154, v151
	v_mul_f32_e32 v77, v140, v159
	v_pk_fma_f32 v[78:79], v[154:155], v[138:139], v[78:79] op_sel_hi:[1,1,0]
	v_mul_f32_e32 v81, v139, v77
	v_mov_b32_e32 v77, v79
	v_mul_f32_e32 v78, v79, v153
	v_pk_fma_f32 v[76:77], v[76:77], v[152:153], v[78:79] op_sel_hi:[1,1,0]
	ds_bpermute_b32 v137, v132, v76
	v_mul_f32_e32 v77, v153, v81
	ds_bpermute_b32 v83, v132, v77
	ds_bpermute_b32 v143, v131, v77
	ds_bpermute_b32 v145, v131, v76
	ds_bpermute_b32 v147, v133, v77
	ds_bpermute_b32 v149, v133, v76
	ds_bpermute_b32 v151, v93, v77
	ds_bpermute_b32 v135, v93, v76
	s_waitcnt lgkmcnt(6)
	v_pk_fma_f32 v[76:77], v[110:111], v[82:83], v[136:137]
	s_waitcnt lgkmcnt(4)
	v_pk_fma_f32 v[76:77], v[76:77], v[142:143], v[144:145]
	s_waitcnt lgkmcnt(2)
	v_pk_fma_f32 v[76:77], v[76:77], v[146:147], v[148:149]
	s_waitcnt lgkmcnt(0)
	v_pk_fma_f32 v[110:111], v[76:77], v[150:151], v[134:135]
	v_pk_mul_f32 v[76:77], v[82:83], v[142:143]
	s_nop 0
	v_pk_mul_f32 v[76:77], v[76:77], v[146:147]
	s_nop 0
	v_pk_mul_f32 v[76:77], v[76:77], v[150:151]
	s_nop 0
	v_pk_mul_f32 v[108:109], v[108:109], v[76:77]
	s_cbranch_scc1 .LBB0_401
	s_mov_b64 s[18:19], 0

.LBB0_405:
	v_add_u32_e32 v97, 0, v135
	v_add_u32_e32 v76, 0x10c00, v97
	ds_read_b128 v[76:79], v76
	v_add_u32_e32 v144, 0x10c40, v97
	ds_read_b128 v[144:147], v144
	s_add_i32 s4, s4, -1
	v_add_u32_e32 v135, 0x1100, v135
	s_cmp_eq_u32 s4, 0
	s_waitcnt lgkmcnt(1)
	v_mfma_f32_16x16x32_bf16 v[80:83], v[76:79], v[0:3], 0
	v_mfma_f32_16x16x32_bf16 v[136:139], v[76:79], v[16:19], 0
	v_mfma_f32_16x16x32_bf16 v[140:143], v[76:79], v[32:35], 0
	v_mfma_f32_16x16x32_bf16 v[76:79], v[76:79], v[48:51], 0
	s_waitcnt lgkmcnt(0)
	v_mfma_f32_16x16x32_bf16 v[80:83], v[144:147], v[4:7], v[80:83]
	v_mfma_f32_16x16x32_bf16 v[136:139], v[144:147], v[20:23], v[136:139]
	v_mfma_f32_16x16x32_bf16 v[140:143], v[144:147], v[36:39], v[140:143]
	v_mfma_f32_16x16x32_bf16 v[76:79], v[144:147], v[52:55], v[76:79]
	v_add_u32_e32 v144, 0x10c80, v97
	ds_read_b128 v[144:147], v144
	v_add_u32_e32 v97, 0x10cc0, v97
	s_waitcnt lgkmcnt(0)
	v_mfma_f32_16x16x32_bf16 v[80:83], v[144:147], v[8:11], v[80:83]
	v_mfma_f32_16x16x32_bf16 v[136:139], v[144:147], v[24:27], v[136:139]
	v_mfma_f32_16x16x32_bf16 v[140:143], v[144:147], v[40:43], v[140:143]
	v_mfma_f32_16x16x32_bf16 v[76:79], v[144:147], v[56:59], v[76:79]
	ds_read_b128 v[144:147], v97
	s_waitcnt lgkmcnt(0)
	v_mfma_f32_16x16x32_bf16 v[148:151], v[144:147], v[12:15], v[80:83]
	s_nop 7
	v_fmamk_f32 v97, v148, 0xbfb8aa3b, v125
	v_mfma_f32_16x16x32_bf16 v[80:83], v[144:147], v[28:31], v[136:139]
	s_nop 0
	v_exp_f32_e32 v97, v97
	v_mfma_f32_16x16x32_bf16 v[136:139], v[144:147], v[44:47], v[140:143]
	v_add_f32_e32 v97, 1.0, v97
	v_rcp_f32_e32 v97, v97
	s_nop 0
	v_fmamk_f32 v143, v149, 0xbfb8aa3b, v125
	s_nop 0
	v_exp_f32_e32 v143, v143
	s_nop 1
	v_fmamk_f32 v137, v137, 0xbfb8aa3b, v126
	s_nop 0
	v_exp_f32_e32 v137, v137
	v_add_f32_e32 v143, 1.0, v143
	v_rcp_f32_e32 v143, v143
	v_mfma_f32_16x16x32_bf16 v[76:79], v[144:147], v[60:63], v[76:79]
	v_add_f32_e32 v137, 1.0, v137
	v_rcp_f32_e32 v137, v137
	v_mul_f32_e32 v143, v143, v127
	v_exp_f32_e32 v143, v143
	v_fmamk_f32 v136, v136, 0xbfb8aa3b, v126
	v_exp_f32_e32 v136, v136
	v_fma_f32 v144, -v143, v143, 1.0
	v_max_f32_e32 v144, 0, v144
	v_sqrt_f32_e32 v144, v144
	v_mul_f32_e32 v97, v97, v127
	v_add_f32_e32 v136, 1.0, v136
	v_mul_f32_e32 v144, v137, v144
	v_fmamk_f32 v137, v150, 0xbfb8aa3b, v125
	v_exp_f32_e32 v137, v137
	v_fmamk_f32 v138, v138, 0xbfb8aa3b, v126
	v_rcp_f32_e32 v140, v136
	v_exp_f32_e32 v136, v97
	v_add_f32_e32 v137, 1.0, v137
	v_rcp_f32_e32 v137, v137
	v_exp_f32_e32 v138, v138
	v_fma_f32 v97, -v136, v136, 1.0
	v_mul_f32_e32 v137, v137, v127
	v_exp_f32_e32 v149, v137
	v_max_f32_e32 v97, 0, v97
	v_add_f32_e32 v138, 1.0, v138
	v_sqrt_f32_e32 v97, v97
	v_fma_f32 v137, -v149, v149, 1.0
	v_max_f32_e32 v137, 0, v137
	v_rcp_f32_e32 v138, v138
	v_sqrt_f32_e32 v137, v137
	v_add_u32_e32 v142, 0, v134
	v_mul_f32_e32 v97, v140, v97
	ds_read2_b32 v[140:141], v142 offset1:16
	ds_read2_b32 v[146:147], v142 offset0:132 offset1:148
	v_mul_f32_e32 v138, v138, v137
	v_add_u32_e32 v137, 0x400, v142
	v_fmamk_f32 v142, v151, 0xbfb8aa3b, v125
	v_exp_f32_e32 v142, v142
	v_fmamk_f32 v139, v139, 0xbfb8aa3b, v126
	v_exp_f32_e32 v139, v139
	v_add_f32_e32 v142, 1.0, v142
	v_rcp_f32_e32 v142, v142
	v_fmamk_f32 v80, v80, 0xbfb8aa3b, v130
	v_exp_f32_e32 v80, v80
	v_mul_f32_e32 v142, v142, v127
	v_exp_f32_e32 v151, v142
	v_add_f32_e32 v139, 1.0, v139
	v_rcp_f32_e32 v139, v139
	ds_read2_b32 v[152:153], v137 offset0:8 offset1:24
	v_fma_f32 v142, -v151, v151, 1.0
	v_max_f32_e32 v142, 0, v142
	v_sqrt_f32_e32 v142, v142
	ds_read2_b32 v[156:157], v137 offset0:140 offset1:156
	s_waitcnt lgkmcnt(3)
	v_mov_b32_e32 v137, v140
	v_mul_f32_e32 v140, 0, v136
	v_add_f32_e32 v80, 1.0, v80
	v_pk_fma_f32 v[158:159], v[136:137], v[96:97], v[140:141] op_sel_hi:[1,1,0]
	v_rcp_f32_e32 v80, v80
	v_mul_f32_e32 v154, v139, v142
	s_waitcnt lgkmcnt(2)
	v_mov_b32_e32 v142, v146
	v_mov_b32_e32 v145, v159
	v_mul_f32_e32 v140, v146, v144
	v_pk_fma_f32 v[144:145], v[142:143], v[144:145], v[140:141] op_sel_hi:[1,1,0]
	v_mul_f32_e32 v97, v136, v143
	s_waitcnt lgkmcnt(1)
	v_mov_b32_e32 v148, v152
	v_mov_b32_e32 v139, v145
	v_mul_f32_e32 v136, v152, v138
	v_pk_fma_f32 v[136:137], v[148:149], v[138:139], v[136:137] op_sel_hi:[1,1,0]
	v_mul_f32_e32 v80, v80, v128
	s_waitcnt lgkmcnt(0)
	v_mov_b32_e32 v150, v156
	v_mov_b32_e32 v155, v137
	v_mul_f32_e32 v136, v151, v137
	v_fmamk_f32 v76, v76, 0xbfb8aa3b, v129
	v_pk_fma_f32 v[136:137], v[150:151], v[154:155], v[136:137] op_sel_hi:[1,1,0]
	v_exp_f32_e32 v154, v80
	v_exp_f32_e32 v76, v76
	v_fmamk_f32 v77, v77, 0xbfb8aa3b, v129
	v_fma_f32 v80, -v154, v154, 1.0
	v_add_f32_e32 v76, 1.0, v76
	v_max_f32_e32 v80, 0, v80
	v_rcp_f32_e32 v76, v76
	v_sqrt_f32_e32 v80, v80
	v_exp_f32_e32 v77, v77
	v_fmamk_f32 v78, v78, 0xbfb8aa3b, v129
	v_mul_f32_e32 v155, v76, v80
	v_fmamk_f32 v76, v81, 0xbfb8aa3b, v130
	v_exp_f32_e32 v76, v76
	v_add_f32_e32 v77, 1.0, v77
	v_rcp_f32_e32 v80, v77
	v_exp_f32_e32 v78, v78
	v_add_f32_e32 v76, 1.0, v76
	v_rcp_f32_e32 v76, v76
	v_fmamk_f32 v79, v79, 0xbfb8aa3b, v129
	v_add_f32_e32 v78, 1.0, v78
	v_rcp_f32_e32 v78, v78
	v_mul_f32_e32 v76, v76, v128
	v_exp_f32_e32 v77, v76
	v_exp_f32_e32 v79, v79
	v_mul_f32_e32 v97, v149, v97
	v_fma_f32 v76, -v77, v77, 1.0
	v_max_f32_e32 v76, 0, v76
	v_sqrt_f32_e32 v76, v76
	v_add_f32_e32 v79, 1.0, v79
	v_rcp_f32_e32 v79, v79
	v_mul_f32_e32 v97, v151, v97
	v_mul_f32_e32 v80, v80, v76
	v_fmamk_f32 v76, v82, 0xbfb8aa3b, v130
	v_exp_f32_e32 v76, v76
	ds_bpermute_b32 v138, v93, v97
	ds_bpermute_b32 v142, v133, v97
	ds_bpermute_b32 v146, v131, v97
	v_add_f32_e32 v76, 1.0, v76
	v_rcp_f32_e32 v76, v76
	ds_bpermute_b32 v150, v132, v97
	v_mov_b32_e32 v97, v141
	v_mul_f32_e32 v82, v80, v147
	v_mul_f32_e32 v76, v76, v128
	v_exp_f32_e32 v159, v76
	v_mov_b32_e32 v158, v153
	ds_bpermute_b32 v140, v93, v136
	ds_bpermute_b32 v144, v133, v136
	v_fma_f32 v76, -v159, v159, 1.0
	v_max_f32_e32 v76, 0, v76
	v_sqrt_f32_e32 v76, v76
	ds_bpermute_b32 v148, v131, v136
	ds_bpermute_b32 v136, v132, v136
	v_add_u32_e32 v134, 0x2100, v134
	v_mul_f32_e32 v78, v78, v76
	v_fmamk_f32 v76, v83, 0xbfb8aa3b, v130
	s_nop 0
	v_exp_f32_e32 v76, v76
	s_nop 0
	v_add_f32_e32 v76, 1.0, v76
	v_rcp_f32_e32 v76, v76
	s_nop 0
	v_mul_f32_e32 v76, v76, v128
	s_nop 0
	v_exp_f32_e32 v83, v76
	s_nop 0
	v_fma_f32 v76, -v83, v83, 1.0
	v_max_f32_e32 v76, 0, v76
	v_sqrt_f32_e32 v76, v76
	s_nop 0
	v_mul_f32_e32 v152, v79, v76
	v_mul_f32_e32 v76, 0, v154
	v_pk_fma_f32 v[160:161], v[154:155], v[96:97], v[76:77] op_sel_hi:[1,1,0]
	v_mov_b32_e32 v76, v147
	v_mov_b32_e32 v81, v161
	v_pk_fma_f32 v[80:81], v[80:81], v[76:77], v[82:83] op_sel_hi:[1,1,0]
	v_mul_f32_e32 v76, v78, v153
	v_mov_b32_e32 v79, v81
	v_mul_f32_e32 v80, v154, v77
	v_pk_fma_f32 v[76:77], v[78:79], v[158:159], v[76:77] op_sel_hi:[1,1,0]
	v_mov_b32_e32 v82, v157
	v_mov_b32_e32 v153, v77
	v_mul_f32_e32 v76, v77, v83
	v_mul_f32_e32 v78, v159, v80
	v_pk_fma_f32 v[76:77], v[152:153], v[82:83], v[76:77] op_sel_hi:[1,1,0]
	ds_bpermute_b32 v141, v93, v76
	v_mul_f32_e32 v77, v83, v78
	ds_bpermute_b32 v139, v93, v77
	ds_bpermute_b32 v143, v133, v77
	ds_bpermute_b32 v145, v133, v76
	ds_bpermute_b32 v147, v131, v77
	ds_bpermute_b32 v149, v131, v76
	ds_bpermute_b32 v151, v132, v77
	ds_bpermute_b32 v137, v132, v76
	s_waitcnt lgkmcnt(6)
	v_pk_fma_f32 v[76:77], v[110:111], v[138:139], v[140:141]
	s_waitcnt lgkmcnt(4)
	v_pk_fma_f32 v[76:77], v[76:77], v[142:143], v[144:145]
	s_waitcnt lgkmcnt(2)
	v_pk_fma_f32 v[76:77], v[76:77], v[146:147], v[148:149]
	s_waitcnt lgkmcnt(0)
	v_pk_fma_f32 v[110:111], v[76:77], v[150:151], v[136:137]
	v_pk_mul_f32 v[76:77], v[138:139], v[142:143]
	s_nop 0
	v_pk_mul_f32 v[76:77], v[76:77], v[146:147]
	s_nop 0
	v_pk_mul_f32 v[76:77], v[76:77], v[150:151]
	s_nop 0
	v_pk_mul_f32 v[108:109], v[108:109], v[76:77]
	s_cbranch_scc0 .LBB0_405

.LBB0_580:
	s_or_b64 exec, exec, s[14:15]
	s_add_i32 s37, s37, s27
	v_add_u32_e32 v78, s37, v147
	v_mov_b64_e32 v[76:77], s[8:9]
	v_mad_i64_i32 v[76:77], s[14:15], v78, s21, v[76:77]
	s_lshl_b32 s4, s26, 1
	v_lshl_add_u64 v[76:77], v[76:77], 0, s[4:5]
	v_mov_b32_e32 v129, v96
	v_lshl_add_u64 v[76:77], v[76:77], 0, v[128:129]
	s_mov_b64 s[14:15], 0x2800
	v_lshl_add_u64 v[78:79], v[76:77], 0, s[14:15]
	v_add_co_u32_e32 v76, vcc, 0x2000, v76
	s_lshl_b32 s14, s26, 2
	s_nop 0
	v_addc_co_u32_e32 v77, vcc, 0, v77, vcc
	global_load_dwordx4 v[88:91], v[76:77], off offset:2048
	global_load_dwordx4 v[84:87], v[78:79], off offset:16
	s_mov_b32 s15, s5
	v_lshl_add_u64 v[132:133], v[122:123], 0, s[14:15]
	s_mov_b64 s[26:27], 0x2000
	v_lshl_add_u64 v[134:135], v[132:133], 0, s[26:27]
	s_mov_b64 s[26:27], 0x6000
	s_mov_b32 s38, 0
	v_lshl_add_u64 v[136:137], v[132:133], 0, s[68:69]
	v_lshl_add_u64 v[138:139], v[132:133], 0, s[26:27]
	v_lshl_add_u64 v[140:141], v[124:125], 0, s[14:15]
	s_waitcnt vmcnt(0)
	v_mul_f32_e32 v163, 0xbfb8aa3b, v163
	v_mul_f32_e32 v164, 0xbfb8aa3b, v164
	v_mul_f32_e32 v167, 0xbfb8aa3b, v167
	v_mul_f32_e32 v168, 0xbfb8aa3b, v168
	v_mul_f32_e32 v165, 0xbfb8aa3b, v165
	v_mul_f32_e32 v166, 0xbfb8aa3b, v166
	s_branch .LBB0_582

.LBB0_598:
	v_mad_u32_u24 v97, v116, s3, v149
	ds_read_b128 v[98:101], v97
	ds_read_b128 v[92:95], v97 offset:64
	v_add_u32_e32 v117, s14, v161
	v_add_u32_e32 v171, 0xec00, v117
	v_add_u32_e32 v176, 0xf000, v117
	s_waitcnt lgkmcnt(1)
	v_mfma_f32_16x16x32_bf16 v[172:175], v[98:101], v[16:19], 0
	s_addk_i32 s14, 0xdf00
	v_add_u32_e32 v116, -16, v116
	v_add_u32_e32 v195, 0x1f700, v117
	v_mfma_f32_16x16x32_bf16 v[102:105], v[98:101], v[0:3], 0
	v_add_u32_e32 v206, 0x1fd30, v117
	v_add_u32_e32 v207, 0x1fb20, v117
	v_add_u32_e32 v208, 0x1f910, v117
	v_mfma_f32_16x16x32_bf16 v[110:113], v[98:101], v[32:35], 0
	v_add_u32_e32 v209, 0x1fd70, v117
	v_add_u32_e32 v210, 0x1fb60, v117
	v_add_u32_e32 v211, 0x1f950, v117
	v_mfma_f32_16x16x32_bf16 v[106:109], v[98:101], v[48:51], 0
	s_cmp_lg_u32 s14, 0xffff7c00
	s_waitcnt lgkmcnt(0)
	v_mfma_f32_16x16x32_bf16 v[98:101], v[92:95], v[20:23], v[172:175]
	s_nop 2
	ds_read_b128 v[172:175], v97 offset:128
	v_mfma_f32_16x16x32_bf16 v[102:105], v[92:95], v[4:7], v[102:105]
	v_mfma_f32_16x16x32_bf16 v[110:113], v[92:95], v[36:39], v[110:113]
	v_mfma_f32_16x16x32_bf16 v[92:95], v[92:95], v[52:55], v[106:109]
	s_nop 2
	ds_read_b128 v[106:109], v97 offset:192
	s_waitcnt lgkmcnt(1)
	v_mfma_f32_16x16x32_bf16 v[102:105], v[172:175], v[8:11], v[102:105]
	v_add_u32_e32 v97, 0xe800, v117
	v_add_u32_e32 v117, 0x1f740, v117
	v_mfma_f32_16x16x32_bf16 v[110:113], v[172:175], v[40:43], v[110:113]
	v_mfma_f32_16x16x32_bf16 v[98:101], v[172:175], v[24:27], v[98:101]
	v_mfma_f32_16x16x32_bf16 v[92:95], v[172:175], v[56:59], v[92:95]
	ds_read2_b32 v[172:173], v176 offset0:76 offset1:92
	ds_read2_b32 v[174:175], v171 offset0:200 offset1:216
	ds_read2_b32 v[176:177], v171 offset0:68 offset1:84
	ds_read2_b32 v[178:179], v97 offset0:192 offset1:208
	s_waitcnt lgkmcnt(3)
	v_mov_b32_e32 v181, v172
	v_mfma_f32_16x16x32_bf16 v[102:105], v[106:109], v[12:15], v[102:105]
	s_waitcnt lgkmcnt(2)
	v_mov_b32_e32 v182, v175
	s_waitcnt lgkmcnt(0)
	v_mov_b32_e32 v186, v179
	v_mov_b32_e32 v184, v177
	v_mfma_f32_16x16x32_bf16 v[110:113], v[106:109], v[44:47], v[110:113]
	v_mfma_f32_16x16x32_bf16 v[98:101], v[106:109], v[28:31], v[98:101]
	s_nop 0
	v_fmamk_f32 v97, v102, 0xbfb8aa3b, v163
	s_nop 4
	v_fmamk_f32 v102, v110, 0xbfb8aa3b, v164
	v_fmamk_f32 v103, v103, 0xbfb8aa3b, v163
	v_mfma_f32_16x16x32_bf16 v[92:95], v[106:109], v[60:63], v[92:95]
	v_fmamk_f32 v104, v104, 0xbfb8aa3b, v163
	v_fmamk_f32 v105, v105, 0xbfb8aa3b, v163
	v_fmamk_f32 v98, v98, 0xbfb8aa3b, v168
	v_fmamk_f32 v99, v99, 0xbfb8aa3b, v168
	v_fmamk_f32 v100, v100, 0xbfb8aa3b, v168
	s_nop 2
	v_fmamk_f32 v92, v92, 0xbfb8aa3b, v167
	s_nop 0
	s_nop 0
	s_nop 0
	s_nop 0
	s_nop 0
	v_fmamk_f32 v94, v94, 0xbfb8aa3b, v167
	v_fmamk_f32 v101, v101, 0xbfb8aa3b, v168
	s_nop 0
	s_nop 0
	s_nop 0
	s_nop 0
	v_exp_f32_e32 v97, v97
	v_exp_f32_e32 v102, v102
	v_exp_f32_e32 v103, v103
	v_exp_f32_e32 v104, v104
	v_exp_f32_e32 v105, v105
	v_exp_f32_e32 v98, v98
	v_exp_f32_e32 v92, v92
	v_exp_f32_e32 v99, v99
	v_exp_f32_e32 v100, v100
	v_fmamk_f32 v95, v95, 0xbfb8aa3b, v167
	v_exp_f32_e32 v94, v94
	v_exp_f32_e32 v101, v101
	v_exp_f32_e32 v95, v95
	v_add_f32_e32 v97, 1.0, v97
	v_add_f32_e32 v102, 1.0, v102
	v_add_f32_e32 v103, 1.0, v103
	v_add_f32_e32 v104, 1.0, v104
	v_add_f32_e32 v105, 1.0, v105
	v_add_f32_e32 v98, 1.0, v98
	v_add_f32_e32 v92, 1.0, v92
	v_add_f32_e32 v99, 1.0, v99
	v_add_f32_e32 v100, 1.0, v100
	v_rcp_f32_e32 v97, v97
	v_rcp_f32_e32 v109, v102
	v_rcp_f32_e32 v102, v103
	v_rcp_f32_e32 v103, v104
	v_rcp_f32_e32 v104, v105
	v_add_f32_e32 v94, 1.0, v94
	v_add_f32_e32 v101, 1.0, v101
	v_rcp_f32_e32 v98, v98
	v_rcp_f32_e32 v110, v92
	v_rcp_f32_e32 v92, v99
	v_rcp_f32_e32 v99, v100
	v_fmamk_f32 v106, v111, 0xbfb8aa3b, v164
	v_rcp_f32_e32 v111, v94
	v_rcp_f32_e32 v94, v101
	v_add_f32_e32 v95, 1.0, v95
	v_fmamk_f32 v108, v113, 0xbfb8aa3b, v164
	v_rcp_f32_e32 v113, v95
	v_mul_f32_e32 v95, v97, v165
	v_mul_f32_e32 v100, v103, v165
	v_mul_f32_e32 v101, v104, v165
	v_fmamk_f32 v107, v112, 0xbfb8aa3b, v164
	v_mul_f32_e32 v97, v102, v165
	v_mul_f32_e32 v98, v98, v166
	v_mul_f32_e32 v92, v92, v166
	v_mul_f32_e32 v99, v99, v166
	v_fmamk_f32 v93, v93, 0xbfb8aa3b, v167
	v_mul_f32_e32 v94, v94, v166
	v_exp_f32_e32 v179, v95
	v_exp_f32_e32 v175, v100
	v_exp_f32_e32 v180, v101
	v_exp_f32_e32 v107, v107
	v_exp_f32_e32 v108, v108
	v_exp_f32_e32 v177, v97
	v_exp_f32_e32 v187, v98
	v_exp_f32_e32 v185, v92
	v_exp_f32_e32 v183, v99
	v_exp_f32_e32 v106, v106
	v_exp_f32_e32 v93, v93
	v_exp_f32_e32 v92, v94
	v_fma_f32 v94, -v179, v179, 1.0
	v_fma_f32 v97, -v175, v175, 1.0
	v_fma_f32 v98, -v180, v180, 1.0
	v_add_f32_e32 v107, 1.0, v107
	v_add_f32_e32 v108, 1.0, v108
	v_fma_f32 v95, -v177, v177, 1.0
	v_fma_f32 v100, -v187, v187, 1.0
	v_fma_f32 v101, -v185, v185, 1.0
	v_fma_f32 v102, -v183, v183, 1.0
	v_max_f32_e32 v94, 0, v94
	v_max_f32_e32 v97, 0, v97
	v_max_f32_e32 v98, 0, v98
	v_add_f32_e32 v106, 1.0, v106
	v_add_f32_e32 v93, 1.0, v93
	v_rcp_f32_e32 v107, v107
	v_rcp_f32_e32 v105, v108
	v_fma_f32 v103, -v92, v92, 1.0
	v_max_f32_e32 v95, 0, v95
	v_max_f32_e32 v100, 0, v100
	v_max_f32_e32 v101, 0, v101
	v_max_f32_e32 v102, 0, v102
	v_sqrt_f32_e32 v108, v94
	v_sqrt_f32_e32 v97, v97
	v_sqrt_f32_e32 v171, v98
	v_rcp_f32_e32 v106, v106
	v_rcp_f32_e32 v93, v93
	v_max_f32_e32 v103, 0, v103
	v_sqrt_f32_e32 v112, v95
	v_sqrt_f32_e32 v172, v100
	v_sqrt_f32_e32 v188, v101
	v_sqrt_f32_e32 v189, v102
	v_mul_f32_e32 v104, v92, v183
	v_sqrt_f32_e32 v190, v103
	v_mul_f32_e32 v104, v185, v104
	v_mul_f32_e32 v103, v187, v104
	v_mul_f32_e32 v104, v109, v108
	v_mul_f32_e32 v108, v107, v97
	v_mul_f32_e32 v97, v105, v171
	v_mul_f32_e32 v106, v106, v112
	v_mul_f32_e32 v110, v110, v172
	v_mul_f32_e32 v112, v93, v188
	v_mul_f32_e32 v172, v111, v189
	v_pk_mul_f32 v[188:189], v[180:181], v[96:97]
	v_mul_f32_e32 v93, v113, v190
	v_pk_fma_f32 v[190:191], v[180:181], v[96:97], v[188:189] op_sel_hi:[1,1,0]
	v_mov_b32_e32 v97, v173
	v_mov_b32_e32 v109, v191
	v_pk_mul_f32 v[190:191], v[92:93], v[96:97]
	v_pk_mul_f32 v[192:193], v[174:175], v[108:109]
	v_pk_fma_f32 v[198:199], v[92:93], v[96:97], v[190:191] op_sel_hi:[1,1,0]
	v_pk_fma_f32 v[108:109], v[174:175], v[108:109], v[192:193] op_sel_hi:[1,1,0]
	v_mov_b32_e32 v173, v199
	v_mov_b32_e32 v107, v109
	v_pk_mul_f32 v[108:109], v[172:173], v[182:183]
	v_pk_mul_f32 v[198:199], v[176:177], v[106:107]
	v_pk_fma_f32 v[172:173], v[172:173], v[182:183], v[108:109] op_sel_hi:[1,1,0]
	v_pk_fma_f32 v[106:107], v[176:177], v[106:107], v[198:199] op_sel_hi:[1,1,0]
	v_mov_b32_e32 v113, v173
	v_mov_b32_e32 v105, v107
	v_pk_mul_f32 v[106:107], v[112:113], v[184:185]
	v_mul_f32_e32 v99, v180, v175
	v_pk_fma_f32 v[112:113], v[112:113], v[184:185], v[106:107] op_sel_hi:[1,1,0]
	v_mul_f32_e32 v99, v177, v99
	v_mov_b32_e32 v111, v113
	v_pk_mul_f32 v[172:173], v[178:179], v[104:105]
	v_pk_mul_f32 v[204:205], v[110:111], v[186:187]
	v_mul_f32_e32 v95, v179, v99
	v_pk_fma_f32 v[104:105], v[178:179], v[104:105], v[172:173] op_sel:[0,0,1] op_sel_hi:[1,1,0]
	v_pk_fma_f32 v[110:111], v[110:111], v[186:187], v[204:205] op_sel:[0,0,1] op_sel_hi:[1,1,0]
	ds_bpermute_b32 v94, v169, v95
	ds_bpermute_b32 v98, v131, v95
	ds_bpermute_b32 v100, v170, v95
	ds_bpermute_b32 v102, v129, v95
	ds_bpermute_b32 v95, v169, v103
	ds_bpermute_b32 v112, v169, v104
	ds_bpermute_b32 v113, v169, v110
	ds_bpermute_b32 v99, v131, v103
	ds_bpermute_b32 v200, v131, v104
	ds_bpermute_b32 v201, v131, v110
	ds_bpermute_b32 v101, v170, v103
	ds_bpermute_b32 v202, v170, v104
	ds_bpermute_b32 v203, v170, v110
	ds_bpermute_b32 v103, v129, v103
	ds_bpermute_b32 v104, v129, v104
	ds_bpermute_b32 v105, v129, v110
	s_waitcnt lgkmcnt(9)
	v_pk_fma_f32 v[94:95], v[114:115], v[94:95], v[112:113]
	s_nop 0
	v_cndmask_b32_e64 v93, v114, v94, s[50:51]
	s_waitcnt lgkmcnt(6)
	v_pk_fma_f32 v[98:99], v[94:95], v[98:99], v[200:201]
	v_cndmask_b32_e64 v97, v115, v95, s[50:51]
	v_cndmask_b32_e64 v93, v93, v98, s[52:53]
	s_waitcnt lgkmcnt(3)
	v_pk_fma_f32 v[94:95], v[98:99], v[100:101], v[202:203]
	v_cndmask_b32_e64 v97, v97, v99, s[52:53]
	v_cndmask_b32_e64 v93, v93, v94, s[54:55]
	s_waitcnt lgkmcnt(0)
	v_pk_fma_f32 v[114:115], v[94:95], v[102:103], v[104:105]
	v_cndmask_b32_e64 v94, v97, v95, s[54:55]
	v_cndmask_b32_e64 v93, v93, v114, s[48:49]
	v_cndmask_b32_e64 v94, v94, v115, s[48:49]
	v_fmac_f32_e32 v189, v180, v93
	v_fmac_f32_e32 v191, v92, v94
	v_fmac_f32_e32 v192, v175, v189
	v_fmac_f32_e32 v108, v183, v191
	v_fmac_f32_e32 v198, v177, v192
	v_fmac_f32_e32 v106, v185, v108
	v_fmac_f32_e32 v172, v179, v198
	ds_write_b32 v206, v189
	ds_write_b32 v209, v191
	ds_write_b32 v207, v192
	ds_write_b32 v210, v108
	ds_write_b32 v208, v198
	ds_write_b32 v211, v106
	v_fmac_f32_e32 v204, v187, v106
	ds_write_b32 v195, v172
	ds_write_b32 v117, v204
	s_cbranch_scc1 .LBB0_598
	s_mov_b64 s[14:15], 0

.LBB0_602:
	v_add_u32_e32 v97, 0, v172
	v_add_u32_e32 v92, 0x10c00, v97
	v_add_u32_e32 v98, 0x10c40, v97
	ds_read_b128 v[92:95], v92
	ds_read_b128 v[102:105], v98
	v_add_u32_e32 v173, 0, v171
	v_add_u32_e32 v180, 0x8c00, v173
	s_waitcnt lgkmcnt(1)
	v_mfma_f32_16x16x32_bf16 v[98:101], v[92:95], v[0:3], 0
	s_add_i32 s14, s14, -1
	v_add_u32_e32 v172, 0x1100, v172
	v_add_u32_e32 v171, 0x2100, v171
	v_mfma_f32_16x16x32_bf16 v[110:113], v[92:95], v[32:35], 0
	v_add_u32_e32 v195, 0x400, v173
	s_cmp_eq_u32 s14, 0
	v_mfma_f32_16x16x32_bf16 v[106:109], v[92:95], v[16:19], 0
	v_mfma_f32_16x16x32_bf16 v[92:95], v[92:95], v[48:51], 0
	s_waitcnt lgkmcnt(0)
	v_mfma_f32_16x16x32_bf16 v[114:117], v[102:105], v[4:7], v[98:101]
	v_mfma_f32_16x16x32_bf16 v[98:101], v[102:105], v[36:39], v[110:113]
	s_nop 2
	v_add_u32_e32 v110, 0x10c80, v97
	v_mfma_f32_16x16x32_bf16 v[174:177], v[102:105], v[20:23], v[106:109]
	v_add_u32_e32 v97, 0x10cc0, v97
	v_mfma_f32_16x16x32_bf16 v[106:109], v[102:105], v[52:55], v[92:95]
	ds_read_b128 v[110:113], v110
	s_nop 1
	ds_read_b128 v[92:95], v97
	v_add_u32_e32 v97, 0x8800, v173
	s_waitcnt lgkmcnt(1)
	v_mfma_f32_16x16x32_bf16 v[102:105], v[110:113], v[8:11], v[114:117]
	v_mfma_f32_16x16x32_bf16 v[114:117], v[110:113], v[24:27], v[174:177]
	s_nop 2
	ds_read2_b32 v[174:175], v97 offset1:16
	ds_read2_b32 v[176:177], v97 offset0:132 offset1:148
	ds_read2_b32 v[178:179], v180 offset0:8 offset1:24
	ds_read2_b32 v[180:181], v180 offset0:140 offset1:156
	s_waitcnt lgkmcnt(3)
	v_mov_b32_e32 v183, v174
	v_mfma_f32_16x16x32_bf16 v[98:101], v[110:113], v[40:43], v[98:101]
	s_waitcnt lgkmcnt(0)
	v_mov_b32_e32 v184, v181
	v_mfma_f32_16x16x32_bf16 v[106:109], v[110:113], v[56:59], v[106:109]
	v_mfma_f32_16x16x32_bf16 v[102:105], v[92:95], v[12:15], v[102:105]
	v_mfma_f32_16x16x32_bf16 v[110:113], v[92:95], v[28:31], v[114:117]
	v_mfma_f32_16x16x32_bf16 v[98:101], v[92:95], v[44:47], v[98:101]
	s_nop 5
	v_fmamk_f32 v97, v102, 0xbfb8aa3b, v163
	v_fmamk_f32 v102, v103, 0xbfb8aa3b, v163
	v_fmamk_f32 v103, v104, 0xbfb8aa3b, v163
	v_mfma_f32_16x16x32_bf16 v[92:95], v[92:95], v[60:63], v[106:109]
	v_fmamk_f32 v104, v105, 0xbfb8aa3b, v163
	v_fmamk_f32 v98, v98, 0xbfb8aa3b, v164
	v_fmamk_f32 v99, v99, 0xbfb8aa3b, v164
	v_fmamk_f32 v100, v100, 0xbfb8aa3b, v164
	v_fmamk_f32 v101, v101, 0xbfb8aa3b, v164
	v_fmamk_f32 v105, v110, 0xbfb8aa3b, v168
	s_nop 1
	v_fmamk_f32 v92, v92, 0xbfb8aa3b, v167
	v_fmamk_f32 v106, v111, 0xbfb8aa3b, v168
	s_nop 0
	v_fmamk_f32 v93, v93, 0xbfb8aa3b, v167
	v_fmamk_f32 v107, v112, 0xbfb8aa3b, v168
	v_fmamk_f32 v94, v94, 0xbfb8aa3b, v167
	v_fmamk_f32 v108, v113, 0xbfb8aa3b, v168
	v_exp_f32_e32 v97, v97
	v_exp_f32_e32 v98, v98
	v_exp_f32_e32 v102, v102
	v_exp_f32_e32 v99, v99
	v_exp_f32_e32 v103, v103
	v_exp_f32_e32 v100, v100
	v_exp_f32_e32 v104, v104
	v_exp_f32_e32 v101, v101
	v_exp_f32_e32 v105, v105
	v_exp_f32_e32 v92, v92
	v_exp_f32_e32 v106, v106
	v_fmamk_f32 v95, v95, 0xbfb8aa3b, v167
	v_exp_f32_e32 v93, v93
	v_exp_f32_e32 v107, v107
	v_exp_f32_e32 v94, v94
	v_exp_f32_e32 v108, v108
	v_exp_f32_e32 v95, v95
	v_add_f32_e32 v97, 1.0, v97
	v_add_f32_e32 v98, 1.0, v98
	v_add_f32_e32 v102, 1.0, v102
	v_add_f32_e32 v99, 1.0, v99
	v_add_f32_e32 v103, 1.0, v103
	v_add_f32_e32 v100, 1.0, v100
	v_add_f32_e32 v104, 1.0, v104
	v_add_f32_e32 v101, 1.0, v101
	v_add_f32_e32 v105, 1.0, v105
	v_add_f32_e32 v92, 1.0, v92
	v_add_f32_e32 v106, 1.0, v106
	v_rcp_f32_e32 v97, v97
	v_add_f32_e32 v93, 1.0, v93
	v_add_f32_e32 v107, 1.0, v107
	v_add_f32_e32 v94, 1.0, v94
	v_add_f32_e32 v108, 1.0, v108
	v_rcp_f32_e32 v109, v98
	v_rcp_f32_e32 v98, v102
	v_rcp_f32_e32 v110, v99
	v_rcp_f32_e32 v99, v103
	v_rcp_f32_e32 v111, v100
	v_rcp_f32_e32 v100, v104
	v_rcp_f32_e32 v112, v101
	v_rcp_f32_e32 v101, v105
	v_rcp_f32_e32 v105, v92
	v_rcp_f32_e32 v92, v106
	v_rcp_f32_e32 v113, v93
	v_rcp_f32_e32 v93, v107
	v_rcp_f32_e32 v107, v94
	v_rcp_f32_e32 v94, v108
	v_add_f32_e32 v95, 1.0, v95
	v_rcp_f32_e32 v174, v95
	v_mul_f32_e32 v95, v97, v165
	v_mul_f32_e32 v97, v98, v165
	v_mul_f32_e32 v98, v99, v165
	v_mul_f32_e32 v99, v100, v165
	v_mul_f32_e32 v100, v101, v166
	v_mul_f32_e32 v92, v92, v166
	v_mul_f32_e32 v93, v93, v166
	v_mul_f32_e32 v94, v94, v166
	v_mov_b32_e32 v101, v92
	v_exp_f32_e32 v182, v95
	v_mov_b32_e32 v114, v177
	v_exp_f32_e32 v177, v97
	v_exp_f32_e32 v92, v100
	v_exp_f32_e32 v115, v101
	v_exp_f32_e32 v181, v99
	v_exp_f32_e32 v117, v93
	v_exp_f32_e32 v185, v94
	v_mov_b32_e32 v116, v179
	v_exp_f32_e32 v179, v98
	v_fma_f32 v93, -v182, v182, 1.0
	v_fma_f32 v94, -v177, v177, 1.0
	v_fma_f32 v99, -v92, v92, 1.0
	v_fma_f32 v100, -v115, v115, 1.0
	v_max_f32_e32 v93, 0, v93
	v_fma_f32 v97, -v181, v181, 1.0
	v_fma_f32 v101, -v117, v117, 1.0
	v_fma_f32 v102, -v185, v185, 1.0
	v_max_f32_e32 v94, 0, v94
	v_max_f32_e32 v99, 0, v99
	v_max_f32_e32 v100, 0, v100
	v_sqrt_f32_e32 v93, v93
	v_fma_f32 v95, -v179, v179, 1.0
	v_mul_f32_e32 v98, v182, v177
	v_mul_f32_e32 v103, v92, v115
	v_max_f32_e32 v97, 0, v97
	v_max_f32_e32 v101, 0, v101
	v_max_f32_e32 v102, 0, v102
	v_sqrt_f32_e32 v104, v94
	v_sqrt_f32_e32 v186, v99
	v_sqrt_f32_e32 v187, v100
	v_max_f32_e32 v95, 0, v95
	v_mul_f32_e32 v98, v179, v98
	v_mul_f32_e32 v103, v117, v103
	v_sqrt_f32_e32 v108, v97
	v_sqrt_f32_e32 v188, v101
	v_sqrt_f32_e32 v189, v102
	v_sqrt_f32_e32 v106, v95
	v_mul_f32_e32 v95, v181, v98
	v_mul_f32_e32 v97, v185, v103
	ds_bpermute_b32 v94, v129, v95
	ds_bpermute_b32 v98, v170, v95
	ds_bpermute_b32 v100, v131, v95
	ds_bpermute_b32 v102, v169, v95
	ds_bpermute_b32 v95, v129, v97
	ds_bpermute_b32 v99, v170, v97
	ds_bpermute_b32 v101, v131, v97
	ds_bpermute_b32 v103, v169, v97
	v_mul_f32_e32 v97, v109, v93
	v_mul_f32_e32 v104, v110, v104
	v_mul_f32_e32 v93, v105, v186
	v_mul_f32_e32 v110, v113, v187
	v_pk_mul_f32 v[186:187], v[182:183], v[96:97]
	v_mul_f32_e32 v108, v112, v108
	v_mul_f32_e32 v112, v107, v188
	v_mul_f32_e32 v174, v174, v189
	v_pk_fma_f32 v[188:189], v[182:183], v[96:97], v[186:187] op_sel_hi:[1,1,0]
	v_mov_b32_e32 v97, v175
	v_mov_b32_e32 v105, v189
	v_pk_mul_f32 v[188:189], v[92:93], v[96:97]
	v_pk_mul_f32 v[190:191], v[176:177], v[104:105]
	v_pk_fma_f32 v[192:193], v[92:93], v[96:97], v[188:189] op_sel_hi:[1,1,0]
	v_mul_f32_e32 v106, v111, v106
	v_pk_fma_f32 v[104:105], v[176:177], v[104:105], v[190:191] op_sel_hi:[1,1,0]
	v_mov_b32_e32 v111, v193
	v_mov_b32_e32 v107, v105
	v_pk_mul_f32 v[104:105], v[110:111], v[114:115]
	v_pk_mul_f32 v[192:193], v[178:179], v[106:107]
	v_pk_fma_f32 v[110:111], v[110:111], v[114:115], v[104:105] op_sel_hi:[1,1,0]
	v_pk_fma_f32 v[106:107], v[178:179], v[106:107], v[192:193] op_sel_hi:[1,1,0]
	v_mov_b32_e32 v113, v111
	v_mov_b32_e32 v109, v107
	v_pk_mul_f32 v[106:107], v[112:113], v[116:117]
	v_pk_mul_f32 v[110:111], v[180:181], v[108:109]
	v_pk_fma_f32 v[112:113], v[112:113], v[116:117], v[106:107] op_sel_hi:[1,1,0]
	v_pk_fma_f32 v[108:109], v[180:181], v[108:109], v[110:111] op_sel:[0,0,1] op_sel_hi:[1,1,0]
	v_mov_b32_e32 v175, v113
	v_pk_mul_f32 v[202:203], v[174:175], v[184:185]
	ds_bpermute_b32 v112, v129, v108
	v_pk_fma_f32 v[174:175], v[174:175], v[184:185], v[202:203] op_sel:[0,0,1] op_sel_hi:[1,1,0]
	ds_bpermute_b32 v113, v129, v174
	ds_bpermute_b32 v198, v170, v108
	ds_bpermute_b32 v199, v170, v174
	ds_bpermute_b32 v200, v131, v108
	ds_bpermute_b32 v201, v131, v174
	ds_bpermute_b32 v108, v169, v108
	ds_bpermute_b32 v109, v169, v174
	s_waitcnt lgkmcnt(6)
	v_pk_fma_f32 v[94:95], v[142:143], v[94:95], v[112:113]
	s_nop 0
	v_cndmask_b32_e64 v93, v142, v94, s[58:59]
	s_waitcnt lgkmcnt(4)
	v_pk_fma_f32 v[98:99], v[94:95], v[98:99], v[198:199]
	v_cndmask_b32_e64 v97, v143, v95, s[58:59]
	v_cndmask_b32_e64 v93, v93, v98, s[60:61]
	s_waitcnt lgkmcnt(2)
	v_pk_fma_f32 v[94:95], v[98:99], v[100:101], v[200:201]
	v_cndmask_b32_e64 v97, v97, v99, s[60:61]
	v_cndmask_b32_e64 v93, v93, v94, s[62:63]
	s_waitcnt lgkmcnt(0)
	v_pk_fma_f32 v[142:143], v[94:95], v[102:103], v[108:109]
	v_cndmask_b32_e64 v94, v97, v95, s[62:63]
	v_cndmask_b32_e64 v93, v93, v142, s[56:57]
	v_cndmask_b32_e64 v94, v94, v143, s[56:57]
	v_fmac_f32_e32 v187, v182, v93
	v_fmac_f32_e32 v189, v92, v94
	v_fmac_f32_e32 v190, v177, v187
	v_fmac_f32_e32 v104, v115, v189
	v_fmac_f32_e32 v192, v179, v190
	v_fmac_f32_e32 v106, v117, v104
	v_fmac_f32_e32 v110, v181, v192
	v_fmac_f32_e32 v202, v185, v106
	ds_write2_b32 v173, v187, v189 offset1:16
	ds_write2_b32 v173, v190, v104 offset0:132 offset1:148
	ds_write2_b32 v195, v192, v106 offset0:8 offset1:24
	ds_write2_b32 v195, v110, v202 offset0:140 offset1:156
	s_cbranch_scc0 .LBB0_602
	s_branch .LBB0_581
